# P0 weight transposes: the three consecutive w_in tiles of a workgroup are loaded together (second and third tile's HBM latency behind the first)
# speedup vs baseline: 1.0041x; 1.0041x over previous
; DI void weight_tile(const Params& p, int id, float* ldsf, int tid) {
;     unsigned char* ws = p.ws;
;     bf16_t* wt1 = (bf16_t*)(ws + OFF_WT1);
;     bf16_t* wz = (bf16_t*)(ws + OFF_WZ);
;     bf16_t* wg = (bf16_t*)(ws + OFF_WG);
;     if (id < WJ5) {
;         int nt, kt, n0, nvalid = 64, nwrite = 64, col0;
;         if (id < WJ0) { nt = id >> 4; kt = id & 15; n0 = nt * 64; col0 = nt * 64; }
;         else if (id < WJ1) { const int j = id - WJ0; nt = j >> 4; kt = j & 15; n0 = 256 + nt * 64; col0 = 1440 + nt * 64; }
;         else if (id < WJ2) { const int j = id - WJ1; nt = j >> 4; kt = j & 15; n0 = 3328 + nt * 64; col0 = 256 + nt * 64; }
;         else if (id < WJ3) { kt = id - WJ2; n0 = 3456; col0 = 384; nvalid = 32; nwrite = 32; }
;         else if (id < WJ4) { kt = id - WJ3; n0 = 3488; col0 = 4512; nvalid = 16; nwrite = 64; }
;         else { kt = id - WJ4; n0 = 3552; col0 = 0; nvalid = 0; nwrite = 32; }
;         transpose_tile(wt1, 1024, n0, nvalid, nwrite, p.w_in, 7600, col0, kt * 64, p.pre_g, ldsf, tid);
;     } else if (id < WJ6) { const int j = id - WJ5; transpose_tile(wz, 1024, (j >> 4) * 64, 64, 64, p.w_in, 7600, 416 + (j >> 4) * 64, (j & 15) * 64, p.pre_g, ldsf, tid); }
; DI void phase0(const Params& p, unsigned char* smem, int tid) {
;     ...
;     {
;         float* ldsf = (float*)(smem + LDS_MISC);
;         const int nw = (gridDim.x == 256) ? W_EARLY : W_ALL;
;         for (int id = bid; id < nw; id += nblk) weight_tile(p, id, ldsf, tid);
;     }
.LBB0_65:
	s_or_b64 exec, exec, s[12:13]
	s_cmpk_eq_i32 s2, 0x100
	s_movk_i32 s3, 0x390
	s_cselect_b32 s3, s3, 0xb30
	s_cmp_ge_i32 s64, s3
	s_cbranch_scc1 .LBB0_154
	s_add_u32 s26, s56, 0x2cfc00
	s_addc_u32 s27, s57, 0
	s_add_u32 s28, s56, 0x9cfc00
	s_addc_u32 s29, s57, 0
	s_waitcnt lgkmcnt(0)
	s_load_dwordx8 s[8:15], s[0:1], 0x28
	s_add_u32 s30, s56, 0xdcfc00
	s_addc_u32 s31, s57, 0
	v_lshlrev_b32_e32 v1, 2, v0
	s_add_u32 s34, s56, 0x128fc00
	v_and_b32_e32 v2, 60, v1
	s_addc_u32 s35, s57, 0
	s_load_dwordx4 s[20:23], s[0:1], 0x10
	v_mov_b32_e32 v9, 0
	v_lshlrev_b32_e32 v8, 2, v2
	s_waitcnt lgkmcnt(0)
	s_cmp_lg_u64 s[10:11], 0
	v_lshl_add_u64 v[10:11], s[14:15], 0, v[8:9]
	s_cselect_b64 s[14:15], -1, 0
	s_add_u32 s36, s56, 0x11cfc00
	s_addc_u32 s37, s57, 0
	v_add_u32_e32 v4, 0x200, v0
	s_cmp_lg_u64 s[8:9], 0
	v_ashrrev_i32_e32 v19, 4, v0
	s_movk_i32 s4, 0x104
	v_ashrrev_i32_e32 v21, 4, v4
	v_ashrrev_i32_e32 v24, 3, v0
	v_and_b32_e32 v0, 7, v0
	v_lshl_add_u64 v[12:13], s[12:13], 0, v[8:9]
	s_cselect_b64 s[12:13], -1, 0
	s_cmp_lg_u64 s[20:21], 0
	v_add_u32_e32 v1, 0, v8
	v_mul_lo_u32 v3, v19, s4
	v_mul_lo_u32 v4, v21, s4
	v_mul_u32_u24_e32 v5, 0x820, v0
	v_lshlrev_b32_e32 v6, 2, v24
	s_cselect_b64 s[38:39], -1, 0
	s_lshl_b32 s6, s64, 2
	v_add3_u32 v5, 0, v5, v6
	v_lshlrev_b32_e32 v0, 3, v0
	s_add_i32 s16, s6, 0xffffdf40
	s_lshl_b32 s6, s64, 4
	v_add_u32_e32 v3, v1, v3
	v_add_u32_e32 v1, v1, v4
	s_mov_b32 s25, 0
	v_cmp_gt_i32_e64 s[4:5], 64, v24
	v_add_u32_e32 v25, 0x400, v24
	v_lshl_add_u64 v[14:15], s[22:23], 0, v[8:9]
	s_lshl_b32 s17, s2, 2
	s_lshl_b32 s33, s64, 6
	s_lshl_b32 s48, s2, 6
	s_add_i32 s49, s6, 0x7fff8700
	s_lshl_b32 s50, s2, 4
	s_movk_i32 s51, 0x50
	v_add_u32_e32 v26, 0x800, v3
	v_add_u32_e32 v27, 0x808, v3
	v_add_u32_e32 v28, 0x800, v1
	v_add_u32_e32 v29, 0x808, v1
	s_mov_b32 s52, 0x150fc00
	s_movk_i32 s53, 0x1800
	s_mov_b64 s[40:41], 0x56c0
	s_movk_i32 s54, 0x76c0
	s_mov_b64 s[42:43], 0x46c0
	v_lshlrev_b32_e32 v16, 2, v2
	v_add_u32_e32 v30, 0x800, v5
	v_add_u32_e32 v31, 0xc00, v5
	v_lshlrev_b32_e32 v8, 1, v0
	v_cndmask_b32_e64 v32, 0, 1, s[14:15]
	s_mov_b32 s98, 0
	s_mov_b32 s55, s64
	s_branch .LBB0_70

; DI void transpose_tile(bf16_t* dst, int dst_ld, int n0, int nvalid, int nwrite, const float* src, int src_ld, int col0, int k0,
;                        const float* gain, float* ldsf, int tid) {
;     ...
;         for (int r = 0; r < 2; ++r) {
;             const int c = tid + NT * r, kk = c >> 4, n4 = (c & 15) * 4;
;             f32x4 v = __builtin_nontemporal_load((const f32x4*)(src + (size_t)(k0 + kk) * src_ld + col0 + n4));
;             const float g = gain ? gain[k0 + kk] : 1.0f;
;             float* d = ldsf + kk * 65 + n4;
;             d[0] = v[0] * g; d[1] = v[1] * g; d[2] = v[2] * g; d[3] = v[3] * g;
;         }
; DI void weight_tile(const Params& p, int id, float* ldsf, int tid) {
;     ...
;         else if (id < WJ1) { const int j = id - WJ0; nt = j >> 4; kt = j & 15; n0 = 256 + nt * 64; col0 = 1440 + nt * 64; }
.LBB0_144:
	s_cmp_lg_u32 s98, 0
	s_cbranch_scc1 .Lwp_use
	s_ashr_i32 s45, s44, 31
	v_lshl_add_u64 v[4:5], s[44:45], 2, v[14:15]
	v_add_u32_e32 v6, s46, v19
	v_mad_i64_i32 v[0:1], s[6:7], v6, s54, v[4:5]
	v_mov_b64_e32 v[36:37], v[0:1]
	global_load_dwordx4 v[0:3], v[0:1], off nt
	v_cndmask_b32_e64 v7, 0, 1, s[38:39]
	v_mov_b32_e32 v18, 1.0
	v_cmp_ne_u32_e64 s[6:7], 1, v7
	s_andn2_b64 vcc, exec, s[38:39]
	v_mov_b32_e32 v20, 1.0
	s_cbranch_vccnz .LBB0_146
	v_ashrrev_i32_e32 v7, 31, v6
	v_lshl_add_u64 v[6:7], v[6:7], 2, s[20:21]
	global_load_dword v20, v[6:7], off
.LBB0_146:
	v_add_u32_e32 v22, s46, v21
	v_mad_i64_i32 v[4:5], s[44:45], v22, s54, v[4:5]
	v_mov_b64_e32 v[38:39], v[4:5]
	global_load_dwordx4 v[4:7], v[4:5], off nt
	s_waitcnt vmcnt(1)
	v_pk_mul_f32 v[0:1], v[0:1], v[20:21] op_sel_hi:[1,0]
	ds_write2_b32 v26, v0, v1 offset1:1
	v_pk_mul_f32 v[0:1], v[2:3], v[20:21] op_sel_hi:[1,0]
	s_and_b64 vcc, exec, s[6:7]
	ds_write2_b32 v27, v0, v1 offset1:1
	s_cbranch_vccnz .LBB0_148
	v_ashrrev_i32_e32 v23, 31, v22
	v_lshl_add_u64 v[0:1], v[22:23], 2, s[20:21]
	global_load_dword v18, v[0:1], off
.LBB0_148:
	s_cmpk_lg_i32 s2, 0x100
	s_cbranch_scc1 .Lwp_nopf
	s_cmp_lt_u32 s55, 64
	s_cbranch_scc1 .Lwp_nopf
	s_cmpk_lt_u32 s55, 0x140
	s_cbranch_scc0 .Lwp_nopf
	s_mov_b64 s[100:101], 0x1000
	v_lshl_add_u64 v[36:37], v[36:37], 0, s[100:101]
	v_lshl_add_u64 v[38:39], v[38:39], 0, s[100:101]
	global_load_dwordx4 v[40:43], v[36:37], off nt
	global_load_dwordx4 v[44:47], v[38:39], off nt
	v_lshl_add_u64 v[36:37], v[36:37], 0, s[100:101]
	v_lshl_add_u64 v[38:39], v[38:39], 0, s[100:101]
	global_load_dwordx4 v[48:51], v[36:37], off nt
	global_load_dwordx4 v[52:55], v[38:39], off nt
	s_mov_b32 s98, 2
	s_waitcnt vmcnt(4)
	s_branch .Lwp_go

; DI void transpose_tile(bf16_t* dst, int dst_ld, int n0, int nvalid, int nwrite, const float* src, int src_ld, int col0, int k0,
;                        const float* gain, float* ldsf, int tid) {
;     ...
;         for (int r = 0; r < 2; ++r) {
;             const int c = tid + NT * r, kk = c >> 4, n4 = (c & 15) * 4;
;             f32x4 v = __builtin_nontemporal_load((const f32x4*)(src + (size_t)(k0 + kk) * src_ld + col0 + n4));
;             const float g = gain ? gain[k0 + kk] : 1.0f;
;             float* d = ldsf + kk * 65 + n4;
;             d[0] = v[0] * g; d[1] = v[1] * g; d[2] = v[2] * g; d[3] = v[3] * g;
;         }
.Lwp_go:
	v_pk_mul_f32 v[0:1], v[4:5], v[18:19] op_sel_hi:[1,0]
	ds_write2_b32 v28, v0, v1 offset1:1
	v_pk_mul_f32 v[0:1], v[6:7], v[18:19] op_sel_hi:[1,0]
	ds_write2_b32 v29, v0, v1 offset1:1
	s_branch .LBB0_149
.Lwp_use:
	s_cmp_eq_u32 s98, 2
	s_cbranch_scc0 .Lwp_use2
	s_waitcnt vmcnt(2)
	v_mov_b64_e32 v[0:1], v[40:41]
	v_mov_b64_e32 v[2:3], v[42:43]
	v_mov_b64_e32 v[4:5], v[44:45]
	v_mov_b64_e32 v[6:7], v[46:47]
	s_mov_b32 s98, 1
	s_branch .Lwp_mul
.Lwp_use2:
	s_waitcnt vmcnt(1)
	v_mov_b64_e32 v[0:1], v[48:49]
	v_mov_b64_e32 v[2:3], v[50:51]
	v_mov_b64_e32 v[4:5], v[52:53]
	v_mov_b64_e32 v[6:7], v[54:55]
	s_mov_b32 s98, 0
.Lwp_mul:
	v_pk_mul_f32 v[34:35], v[0:1], v[20:21] op_sel_hi:[1,0]
	ds_write2_b32 v26, v34, v35 offset1:1
	v_pk_mul_f32 v[34:35], v[2:3], v[20:21] op_sel_hi:[1,0]
	ds_write2_b32 v27, v34, v35 offset1:1
	v_pk_mul_f32 v[34:35], v[4:5], v[18:19] op_sel_hi:[1,0]
	ds_write2_b32 v28, v34, v35 offset1:1
	v_pk_mul_f32 v[34:35], v[6:7], v[18:19] op_sel_hi:[1,0]
	ds_write2_b32 v29, v34, v35 offset1:1
